# phase_convert_late rewritten by hand as one routine for its three call sites: 16 loads per thread in flight, next tile prefetched, one barrier per tile, tiles dealt to 640 slots (2 per idle block)
# speedup vs baseline: 1.0153x; 1.0153x over previous
.LBB0_207:
	s_and_b64 vcc, exec, s[2:3]
	s_cbranch_vccz .LBB0_385
	v_readlane_b32 s6, v237, 0
	s_cmpk_gt_i32 s6, 0x7f
	s_mov_b64 s[0:1], -1
	s_cbranch_scc0 .LBB0_269
	s_cmpk_gt_u32 s6, 0x17f
	s_cbranch_scc0 .LBB0_265
	s_add_i32 s7, s6, 0xfffffe80
	s_add_i32 s19, s7, 0x80
	s_branch .Lcl_entry

.LBB0_276:
	v_mov_b32_e32 v0, v163
	s_barrier
	s_add_i32 s7, s6, 0x100
	s_mov_b32 s19, 0x10000
	s_branch .Lcl_entry

.Lpp_done:
	v_mov_b32_e32 v0, v163
	s_barrier
	s_add_i32 s7, s6, 0x100
	s_mov_b32 s19, 0x10000
.Lcl_entry:
	v_and_b32_e32 v2, 63, v163
	v_lshrrev_b32_e32 v3, 6, v163
	v_lshrrev_b32_e32 v4, 3, v163
	v_and_b32_e32 v5, 7, v163
	v_lshlrev_b32_e32 v5, 3, v5
	v_mul_u32_u24_e32 v18, 0x41, v2
	v_add_u32_e32 v18, v18, v3
	v_lshlrev_b32_e32 v6, 2, v18
	v_add_u32_e32 v7, 0x4100, v6
	v_mul_u32_u24_e32 v18, 0x41, v4
	v_add_u32_e32 v18, v18, v5
	v_lshlrev_b32_e32 v8, 2, v18
	v_add_u32_e32 v9, 0x2080, v8
	v_add_u32_e32 v10, 0x4100, v8
	v_add_u32_e32 v11, 0x4100, v9
	s_cmpk_ge_u32 s7, 2880
	s_cbranch_scc1 .Lcl_done
	s_cmpk_lt_u32 s7, 256
	s_cbranch_scc1 .Lcl_j0_0
	s_cmpk_lt_u32 s7, 384
	s_cbranch_scc1 .Lcl_j1_0
	s_cmpk_lt_u32 s7, 512
	s_cbranch_scc1 .Lcl_j2_0
	s_cmpk_lt_u32 s7, 768
	s_cbranch_scc1 .Lcl_j3_0
	s_cmpk_lt_u32 s7, 2176
	s_cbranch_scc1 .Lcl_j4_0
	v_readlane_b32 s8, v235, 10
	v_readlane_b32 s9, v235, 11
	s_mov_b32 s10, s58
	s_mov_b32 s11, s59
	s_mov_b32 s12, 0x1000
	s_movk_i32 s13, 0x1680
	s_movk_i32 s16, 0
	s_sub_u32 s17, s7, 2176
	s_mul_i32 s15, s17, 1490
	s_lshr_b32 s15, s15, 16
	s_mul_i32 s18, s15, 44
	s_sub_u32 s14, s17, s18
	s_branch .Lcl_jc_0
.Lcl_j0_0:
	v_readlane_b32 s8, v235, 0
	v_readlane_b32 s9, v235, 1
	s_mov_b32 s10, s48
	s_mov_b32 s11, s49
	s_mov_b32 s12, 0x2000
	s_movk_i32 s13, 0x480
	s_movk_i32 s16, 0
	s_mov_b32 s17, s7
	s_and_b32 s14, s17, 7
	s_lshr_b32 s15, s17, 3
	s_branch .Lcl_jc_0
.Lcl_j1_0:
	v_readlane_b32 s8, v235, 2
	v_readlane_b32 s9, v235, 3
	s_mov_b32 s10, s50
	s_mov_b32 s11, s51
	s_mov_b32 s12, 0x1000
	s_movk_i32 s13, 0x480
	s_movk_i32 s16, 0
	s_sub_u32 s17, s7, 256
	s_and_b32 s14, s17, 7
	s_lshr_b32 s15, s17, 3
	s_branch .Lcl_jc_0
.Lcl_j2_0:
	v_readlane_b32 s8, v235, 4
	v_readlane_b32 s9, v235, 5
	s_mov_b32 s10, s52
	s_mov_b32 s11, s53
	s_mov_b32 s12, 0x1000
	s_movk_i32 s13, 0x480
	s_movk_i32 s16, 0
	s_sub_u32 s17, s7, 384
	s_and_b32 s14, s17, 7
	s_lshr_b32 s15, s17, 3
	s_branch .Lcl_jc_0
.Lcl_j3_0:
	v_readlane_b32 s8, v235, 6
	v_readlane_b32 s9, v235, 7
	s_mov_b32 s10, s54
	s_mov_b32 s11, s55
	s_mov_b32 s12, 0x1000
	s_movk_i32 s13, 0x880
	s_movk_i32 s16, 0
	s_sub_u32 s17, s7, 512
	s_and_b32 s14, s17, 15
	s_lshr_b32 s15, s17, 4
	s_branch .Lcl_jc_0
.Lcl_j4_0:
	v_readlane_b32 s8, v235, 8
	v_readlane_b32 s9, v235, 9
	s_mov_b32 s10, s56
	s_mov_b32 s11, s57
	s_mov_b32 s12, 0x5800
	s_movk_i32 s13, 0x880
	s_movk_i32 s16, 1
	s_sub_u32 s17, s7, 768
	s_and_b32 s14, s17, 15
	s_lshr_b32 s15, s17, 4
.Lcl_jc_0:
	s_lshl_b32 s17, s14, 6
	s_mul_i32 s17, s17, s12
	s_add_u32 s8, s8, s17
	s_addc_u32 s9, s9, 0
	s_lshl_b32 s17, s15, 6
	s_mul_i32 s17, s17, s13
	s_lshl_b32 s18, s14, 7
	s_add_u32 s17, s17, s18
	s_add_u32 s10, s10, s17
	s_addc_u32 s11, s11, 0
	s_lshl_b32 s17, s15, 6
	v_add_u32_e32 v18, s17, v2
	v_bfe_u32 v19, v18, 5, 1
	v_mul_u32_u24_e32 v19, 0xb00, v19
	v_lshrrev_b32_e32 v20, 7, v18
	v_lshl_add_u32 v19, v20, 6, v19
	v_bfe_u32 v20, v18, 6, 1
	v_lshl_add_u32 v19, v20, 5, v19
	v_bfe_u32 v20, v18, 4, 1
	v_lshl_add_u32 v19, v20, 4, v19
	v_and_b32_e32 v20, 15, v18
	v_add_u32_e32 v19, v19, v20
	s_cmp_eq_u32 s16, 1
	s_cselect_b64 s[24:25], -1, 0
	s_nop 1
	v_cndmask_b32_e64 v18, v18, v19, s[24:25]
	v_mul_lo_u32 v19, v3, s12
	v_lshl_add_u32 v12, v18, 2, v19
	v_mul_lo_u32 v19, v4, s13
	v_lshl_add_u32 v14, v5, 1, v19
	s_lshl_b32 s17, s13, 5
	v_add_u32_e32 v15, s17, v14
	s_lshl_b32 s17, s12, 2
	global_load_dword v32, v12, s[8:9]
	s_add_u32 s8, s8, s17
	s_addc_u32 s9, s9, 0
	global_load_dword v33, v12, s[8:9]
	s_add_u32 s8, s8, s17
	s_addc_u32 s9, s9, 0
	global_load_dword v34, v12, s[8:9]
	s_add_u32 s8, s8, s17
	s_addc_u32 s9, s9, 0
	global_load_dword v35, v12, s[8:9]
	s_add_u32 s8, s8, s17
	s_addc_u32 s9, s9, 0
	global_load_dword v36, v12, s[8:9]
	s_add_u32 s8, s8, s17
	s_addc_u32 s9, s9, 0
	global_load_dword v37, v12, s[8:9]
	s_add_u32 s8, s8, s17
	s_addc_u32 s9, s9, 0
	global_load_dword v38, v12, s[8:9]
	s_add_u32 s8, s8, s17
	s_addc_u32 s9, s9, 0
	global_load_dword v39, v12, s[8:9]
	s_add_u32 s8, s8, s17
	s_addc_u32 s9, s9, 0
	global_load_dword v40, v12, s[8:9]
	s_add_u32 s8, s8, s17
	s_addc_u32 s9, s9, 0
	global_load_dword v41, v12, s[8:9]
	s_add_u32 s8, s8, s17
	s_addc_u32 s9, s9, 0
	global_load_dword v42, v12, s[8:9]
	s_add_u32 s8, s8, s17
	s_addc_u32 s9, s9, 0
	global_load_dword v43, v12, s[8:9]
	s_add_u32 s8, s8, s17
	s_addc_u32 s9, s9, 0
	global_load_dword v44, v12, s[8:9]
	s_add_u32 s8, s8, s17
	s_addc_u32 s9, s9, 0
	global_load_dword v45, v12, s[8:9]
	s_add_u32 s8, s8, s17
	s_addc_u32 s9, s9, 0
	global_load_dword v46, v12, s[8:9]
	s_add_u32 s8, s8, s17
	s_addc_u32 s9, s9, 0
	global_load_dword v47, v12, s[8:9]
.Lcl_loop:
	s_addk_i32 s7, 0x280
	s_cmpk_ge_u32 s7, 2880
	s_cbranch_scc0 .Lcl_nx0
	s_mov_b32 s7, s19
	s_mov_b32 s19, 0x10000
.Lcl_nx0:
	s_cmpk_ge_u32 s7, 2880
	s_cbranch_scc1 .Lcl_last0
	s_cmpk_lt_u32 s7, 256
	s_cbranch_scc1 .Lcl_j0_1
	s_cmpk_lt_u32 s7, 384
	s_cbranch_scc1 .Lcl_j1_1
	s_cmpk_lt_u32 s7, 512
	s_cbranch_scc1 .Lcl_j2_1
	s_cmpk_lt_u32 s7, 768
	s_cbranch_scc1 .Lcl_j3_1
	s_cmpk_lt_u32 s7, 2176
	s_cbranch_scc1 .Lcl_j4_1
	v_readlane_b32 s20, v235, 10
	v_readlane_b32 s21, v235, 11
	s_mov_b32 s22, s58
	s_mov_b32 s23, s59
	s_mov_b32 s12, 0x1000
	s_movk_i32 s13, 0x1680
	s_movk_i32 s16, 0
	s_sub_u32 s17, s7, 2176
	s_mul_i32 s15, s17, 1490
	s_lshr_b32 s15, s15, 16
	s_mul_i32 s18, s15, 44
	s_sub_u32 s14, s17, s18
	s_branch .Lcl_jc_1
.Lcl_j0_1:
	v_readlane_b32 s20, v235, 0
	v_readlane_b32 s21, v235, 1
	s_mov_b32 s22, s48
	s_mov_b32 s23, s49
	s_mov_b32 s12, 0x2000
	s_movk_i32 s13, 0x480
	s_movk_i32 s16, 0
	s_mov_b32 s17, s7
	s_and_b32 s14, s17, 7
	s_lshr_b32 s15, s17, 3
	s_branch .Lcl_jc_1
.Lcl_j1_1:
	v_readlane_b32 s20, v235, 2
	v_readlane_b32 s21, v235, 3
	s_mov_b32 s22, s50
	s_mov_b32 s23, s51
	s_mov_b32 s12, 0x1000
	s_movk_i32 s13, 0x480
	s_movk_i32 s16, 0
	s_sub_u32 s17, s7, 256
	s_and_b32 s14, s17, 7
	s_lshr_b32 s15, s17, 3
	s_branch .Lcl_jc_1
.Lcl_j2_1:
	v_readlane_b32 s20, v235, 4
	v_readlane_b32 s21, v235, 5
	s_mov_b32 s22, s52
	s_mov_b32 s23, s53
	s_mov_b32 s12, 0x1000
	s_movk_i32 s13, 0x480
	s_movk_i32 s16, 0
	s_sub_u32 s17, s7, 384
	s_and_b32 s14, s17, 7
	s_lshr_b32 s15, s17, 3
	s_branch .Lcl_jc_1
.Lcl_j3_1:
	v_readlane_b32 s20, v235, 6
	v_readlane_b32 s21, v235, 7
	s_mov_b32 s22, s54
	s_mov_b32 s23, s55
	s_mov_b32 s12, 0x1000
	s_movk_i32 s13, 0x880
	s_movk_i32 s16, 0
	s_sub_u32 s17, s7, 512
	s_and_b32 s14, s17, 15
	s_lshr_b32 s15, s17, 4
	s_branch .Lcl_jc_1
.Lcl_j4_1:
	v_readlane_b32 s20, v235, 8
	v_readlane_b32 s21, v235, 9
	s_mov_b32 s22, s56
	s_mov_b32 s23, s57
	s_mov_b32 s12, 0x5800
	s_movk_i32 s13, 0x880
	s_movk_i32 s16, 1
	s_sub_u32 s17, s7, 768
	s_and_b32 s14, s17, 15
	s_lshr_b32 s15, s17, 4
.Lcl_jc_1:
	s_lshl_b32 s17, s14, 6
	s_mul_i32 s17, s17, s12
	s_add_u32 s20, s20, s17
	s_addc_u32 s21, s21, 0
	s_lshl_b32 s17, s15, 6
	s_mul_i32 s17, s17, s13
	s_lshl_b32 s18, s14, 7
	s_add_u32 s17, s17, s18
	s_add_u32 s22, s22, s17
	s_addc_u32 s23, s23, 0
	s_lshl_b32 s17, s15, 6
	v_add_u32_e32 v18, s17, v2
	v_bfe_u32 v19, v18, 5, 1
	v_mul_u32_u24_e32 v19, 0xb00, v19
	v_lshrrev_b32_e32 v20, 7, v18
	v_lshl_add_u32 v19, v20, 6, v19
	v_bfe_u32 v20, v18, 6, 1
	v_lshl_add_u32 v19, v20, 5, v19
	v_bfe_u32 v20, v18, 4, 1
	v_lshl_add_u32 v19, v20, 4, v19
	v_and_b32_e32 v20, 15, v18
	v_add_u32_e32 v19, v19, v20
	s_cmp_eq_u32 s16, 1
	s_cselect_b64 s[24:25], -1, 0
	s_nop 1
	v_cndmask_b32_e64 v18, v18, v19, s[24:25]
	v_mul_lo_u32 v19, v3, s12
	v_lshl_add_u32 v13, v18, 2, v19
	v_mul_lo_u32 v19, v4, s13
	v_lshl_add_u32 v16, v5, 1, v19
	s_lshl_b32 s17, s13, 5
	v_add_u32_e32 v17, s17, v16
	s_lshl_b32 s17, s12, 2
	global_load_dword v48, v13, s[20:21]
	s_add_u32 s20, s20, s17
	s_addc_u32 s21, s21, 0
	global_load_dword v49, v13, s[20:21]
	s_add_u32 s20, s20, s17
	s_addc_u32 s21, s21, 0
	global_load_dword v50, v13, s[20:21]
	s_add_u32 s20, s20, s17
	s_addc_u32 s21, s21, 0
	global_load_dword v51, v13, s[20:21]
	s_add_u32 s20, s20, s17
	s_addc_u32 s21, s21, 0
	global_load_dword v52, v13, s[20:21]
	s_add_u32 s20, s20, s17
	s_addc_u32 s21, s21, 0
	global_load_dword v53, v13, s[20:21]
	s_add_u32 s20, s20, s17
	s_addc_u32 s21, s21, 0
	global_load_dword v54, v13, s[20:21]
	s_add_u32 s20, s20, s17
	s_addc_u32 s21, s21, 0
	global_load_dword v55, v13, s[20:21]
	s_add_u32 s20, s20, s17
	s_addc_u32 s21, s21, 0
	global_load_dword v56, v13, s[20:21]
	s_add_u32 s20, s20, s17
	s_addc_u32 s21, s21, 0
	global_load_dword v57, v13, s[20:21]
	s_add_u32 s20, s20, s17
	s_addc_u32 s21, s21, 0
	global_load_dword v58, v13, s[20:21]
	s_add_u32 s20, s20, s17
	s_addc_u32 s21, s21, 0
	global_load_dword v59, v13, s[20:21]
	s_add_u32 s20, s20, s17
	s_addc_u32 s21, s21, 0
	global_load_dword v60, v13, s[20:21]
	s_add_u32 s20, s20, s17
	s_addc_u32 s21, s21, 0
	global_load_dword v61, v13, s[20:21]
	s_add_u32 s20, s20, s17
	s_addc_u32 s21, s21, 0
	global_load_dword v62, v13, s[20:21]
	s_add_u32 s20, s20, s17
	s_addc_u32 s21, s21, 0
	global_load_dword v63, v13, s[20:21]
	s_waitcnt vmcnt(16)
	ds_write2_b32 v6, v32, v33 offset0:0 offset1:4
	ds_write2_b32 v6, v34, v35 offset0:8 offset1:12
	ds_write2_b32 v6, v36, v37 offset0:16 offset1:20
	ds_write2_b32 v6, v38, v39 offset0:24 offset1:28
	ds_write2_b32 v6, v40, v41 offset0:32 offset1:36
	ds_write2_b32 v6, v42, v43 offset0:40 offset1:44
	ds_write2_b32 v6, v44, v45 offset0:48 offset1:52
	ds_write2_b32 v6, v46, v47 offset0:56 offset1:60
	s_waitcnt lgkmcnt(0)
	s_barrier
	ds_read2_b32 v[64:65], v8 offset0:0 offset1:1
	ds_read2_b32 v[66:67], v8 offset0:2 offset1:3
	ds_read2_b32 v[68:69], v8 offset0:4 offset1:5
	ds_read2_b32 v[70:71], v8 offset0:6 offset1:7
	ds_read2_b32 v[72:73], v9 offset0:0 offset1:1
	ds_read2_b32 v[74:75], v9 offset0:2 offset1:3
	ds_read2_b32 v[76:77], v9 offset0:4 offset1:5
	ds_read2_b32 v[78:79], v9 offset0:6 offset1:7
	s_waitcnt lgkmcnt(4)
	v_cvt_pk_bf16_f32 v80, v64, v65
	v_cvt_pk_bf16_f32 v81, v66, v67
	v_cvt_pk_bf16_f32 v82, v68, v69
	v_cvt_pk_bf16_f32 v83, v70, v71
	global_store_dwordx4 v14, v[80:83], s[10:11]
	s_waitcnt lgkmcnt(0)
	v_cvt_pk_bf16_f32 v84, v72, v73
	v_cvt_pk_bf16_f32 v85, v74, v75
	v_cvt_pk_bf16_f32 v86, v76, v77
	v_cvt_pk_bf16_f32 v87, v78, v79
	global_store_dwordx4 v15, v[84:87], s[10:11]
	s_addk_i32 s7, 0x280
	s_cmpk_ge_u32 s7, 2880
	s_cbranch_scc0 .Lcl_nx1
	s_mov_b32 s7, s19
	s_mov_b32 s19, 0x10000
.Lcl_nx1:
	s_cmpk_ge_u32 s7, 2880
	s_cbranch_scc1 .Lcl_last1
	s_cmpk_lt_u32 s7, 256
	s_cbranch_scc1 .Lcl_j0_2
	s_cmpk_lt_u32 s7, 384
	s_cbranch_scc1 .Lcl_j1_2
	s_cmpk_lt_u32 s7, 512
	s_cbranch_scc1 .Lcl_j2_2
	s_cmpk_lt_u32 s7, 768
	s_cbranch_scc1 .Lcl_j3_2
	s_cmpk_lt_u32 s7, 2176
	s_cbranch_scc1 .Lcl_j4_2
	v_readlane_b32 s8, v235, 10
	v_readlane_b32 s9, v235, 11
	s_mov_b32 s10, s58
	s_mov_b32 s11, s59
	s_mov_b32 s12, 0x1000
	s_movk_i32 s13, 0x1680
	s_movk_i32 s16, 0
	s_sub_u32 s17, s7, 2176
	s_mul_i32 s15, s17, 1490
	s_lshr_b32 s15, s15, 16
	s_mul_i32 s18, s15, 44
	s_sub_u32 s14, s17, s18
	s_branch .Lcl_jc_2

.Lcl_jc_2:
	s_lshl_b32 s17, s14, 6
	s_mul_i32 s17, s17, s12
	s_add_u32 s8, s8, s17
	s_addc_u32 s9, s9, 0
	s_lshl_b32 s17, s15, 6
	s_mul_i32 s17, s17, s13
	s_lshl_b32 s18, s14, 7
	s_add_u32 s17, s17, s18
	s_add_u32 s10, s10, s17
	s_addc_u32 s11, s11, 0
	s_lshl_b32 s17, s15, 6
	v_add_u32_e32 v18, s17, v2
	v_bfe_u32 v19, v18, 5, 1
	v_mul_u32_u24_e32 v19, 0xb00, v19
	v_lshrrev_b32_e32 v20, 7, v18
	v_lshl_add_u32 v19, v20, 6, v19
	v_bfe_u32 v20, v18, 6, 1
	v_lshl_add_u32 v19, v20, 5, v19
	v_bfe_u32 v20, v18, 4, 1
	v_lshl_add_u32 v19, v20, 4, v19
	v_and_b32_e32 v20, 15, v18
	v_add_u32_e32 v19, v19, v20
	s_cmp_eq_u32 s16, 1
	s_cselect_b64 s[24:25], -1, 0
	s_nop 1
	v_cndmask_b32_e64 v18, v18, v19, s[24:25]
	v_mul_lo_u32 v19, v3, s12
	v_lshl_add_u32 v12, v18, 2, v19
	v_mul_lo_u32 v19, v4, s13
	v_lshl_add_u32 v14, v5, 1, v19
	s_lshl_b32 s17, s13, 5
	v_add_u32_e32 v15, s17, v14
	s_lshl_b32 s17, s12, 2
	global_load_dword v32, v12, s[8:9]
	s_add_u32 s8, s8, s17
	s_addc_u32 s9, s9, 0
	global_load_dword v33, v12, s[8:9]
	s_add_u32 s8, s8, s17
	s_addc_u32 s9, s9, 0
	global_load_dword v34, v12, s[8:9]
	s_add_u32 s8, s8, s17
	s_addc_u32 s9, s9, 0
	global_load_dword v35, v12, s[8:9]
	s_add_u32 s8, s8, s17
	s_addc_u32 s9, s9, 0
	global_load_dword v36, v12, s[8:9]
	s_add_u32 s8, s8, s17
	s_addc_u32 s9, s9, 0
	global_load_dword v37, v12, s[8:9]
	s_add_u32 s8, s8, s17
	s_addc_u32 s9, s9, 0
	global_load_dword v38, v12, s[8:9]
	s_add_u32 s8, s8, s17
	s_addc_u32 s9, s9, 0
	global_load_dword v39, v12, s[8:9]
	s_add_u32 s8, s8, s17
	s_addc_u32 s9, s9, 0
	global_load_dword v40, v12, s[8:9]
	s_add_u32 s8, s8, s17
	s_addc_u32 s9, s9, 0
	global_load_dword v41, v12, s[8:9]
	s_add_u32 s8, s8, s17
	s_addc_u32 s9, s9, 0
	global_load_dword v42, v12, s[8:9]
	s_add_u32 s8, s8, s17
	s_addc_u32 s9, s9, 0
	global_load_dword v43, v12, s[8:9]
	s_add_u32 s8, s8, s17
	s_addc_u32 s9, s9, 0
	global_load_dword v44, v12, s[8:9]
	s_add_u32 s8, s8, s17
	s_addc_u32 s9, s9, 0
	global_load_dword v45, v12, s[8:9]
	s_add_u32 s8, s8, s17
	s_addc_u32 s9, s9, 0
	global_load_dword v46, v12, s[8:9]
	s_add_u32 s8, s8, s17
	s_addc_u32 s9, s9, 0
	global_load_dword v47, v12, s[8:9]
	s_waitcnt vmcnt(16)
	ds_write2_b32 v7, v48, v49 offset0:0 offset1:4
	ds_write2_b32 v7, v50, v51 offset0:8 offset1:12
	ds_write2_b32 v7, v52, v53 offset0:16 offset1:20
	ds_write2_b32 v7, v54, v55 offset0:24 offset1:28
	ds_write2_b32 v7, v56, v57 offset0:32 offset1:36
	ds_write2_b32 v7, v58, v59 offset0:40 offset1:44
	ds_write2_b32 v7, v60, v61 offset0:48 offset1:52
	ds_write2_b32 v7, v62, v63 offset0:56 offset1:60
	s_waitcnt lgkmcnt(0)
	s_barrier
	ds_read2_b32 v[64:65], v10 offset0:0 offset1:1
	ds_read2_b32 v[66:67], v10 offset0:2 offset1:3
	ds_read2_b32 v[68:69], v10 offset0:4 offset1:5
	ds_read2_b32 v[70:71], v10 offset0:6 offset1:7
	ds_read2_b32 v[72:73], v11 offset0:0 offset1:1
	ds_read2_b32 v[74:75], v11 offset0:2 offset1:3
	ds_read2_b32 v[76:77], v11 offset0:4 offset1:5
	ds_read2_b32 v[78:79], v11 offset0:6 offset1:7
	s_waitcnt lgkmcnt(4)
	v_cvt_pk_bf16_f32 v80, v64, v65
	v_cvt_pk_bf16_f32 v81, v66, v67
	v_cvt_pk_bf16_f32 v82, v68, v69
	v_cvt_pk_bf16_f32 v83, v70, v71
	global_store_dwordx4 v16, v[80:83], s[22:23]
	s_waitcnt lgkmcnt(0)
	v_cvt_pk_bf16_f32 v84, v72, v73
	v_cvt_pk_bf16_f32 v85, v74, v75
	v_cvt_pk_bf16_f32 v86, v76, v77
	v_cvt_pk_bf16_f32 v87, v78, v79
	global_store_dwordx4 v17, v[84:87], s[22:23]
	s_branch .Lcl_loop
.Lcl_last0:
	s_waitcnt vmcnt(0)
	ds_write2_b32 v6, v32, v33 offset0:0 offset1:4
	ds_write2_b32 v6, v34, v35 offset0:8 offset1:12
	ds_write2_b32 v6, v36, v37 offset0:16 offset1:20
	ds_write2_b32 v6, v38, v39 offset0:24 offset1:28
	ds_write2_b32 v6, v40, v41 offset0:32 offset1:36
	ds_write2_b32 v6, v42, v43 offset0:40 offset1:44
	ds_write2_b32 v6, v44, v45 offset0:48 offset1:52
	ds_write2_b32 v6, v46, v47 offset0:56 offset1:60
	s_waitcnt lgkmcnt(0)
	s_barrier
	ds_read2_b32 v[64:65], v8 offset0:0 offset1:1
	ds_read2_b32 v[66:67], v8 offset0:2 offset1:3
	ds_read2_b32 v[68:69], v8 offset0:4 offset1:5
	ds_read2_b32 v[70:71], v8 offset0:6 offset1:7
	ds_read2_b32 v[72:73], v9 offset0:0 offset1:1
	ds_read2_b32 v[74:75], v9 offset0:2 offset1:3
	ds_read2_b32 v[76:77], v9 offset0:4 offset1:5
	ds_read2_b32 v[78:79], v9 offset0:6 offset1:7
	s_waitcnt lgkmcnt(4)
	v_cvt_pk_bf16_f32 v80, v64, v65
	v_cvt_pk_bf16_f32 v81, v66, v67
	v_cvt_pk_bf16_f32 v82, v68, v69
	v_cvt_pk_bf16_f32 v83, v70, v71
	global_store_dwordx4 v14, v[80:83], s[10:11]
	s_waitcnt lgkmcnt(0)
	v_cvt_pk_bf16_f32 v84, v72, v73
	v_cvt_pk_bf16_f32 v85, v74, v75
	v_cvt_pk_bf16_f32 v86, v76, v77
	v_cvt_pk_bf16_f32 v87, v78, v79
	global_store_dwordx4 v15, v[84:87], s[10:11]
	s_branch .Lcl_done
.Lcl_last1:
	s_waitcnt vmcnt(0)
	ds_write2_b32 v7, v48, v49 offset0:0 offset1:4
	ds_write2_b32 v7, v50, v51 offset0:8 offset1:12
	ds_write2_b32 v7, v52, v53 offset0:16 offset1:20
	ds_write2_b32 v7, v54, v55 offset0:24 offset1:28
	ds_write2_b32 v7, v56, v57 offset0:32 offset1:36
	ds_write2_b32 v7, v58, v59 offset0:40 offset1:44
	ds_write2_b32 v7, v60, v61 offset0:48 offset1:52
	ds_write2_b32 v7, v62, v63 offset0:56 offset1:60
	s_waitcnt lgkmcnt(0)
	s_barrier
	ds_read2_b32 v[64:65], v10 offset0:0 offset1:1
	ds_read2_b32 v[66:67], v10 offset0:2 offset1:3
	ds_read2_b32 v[68:69], v10 offset0:4 offset1:5
	ds_read2_b32 v[70:71], v10 offset0:6 offset1:7
	ds_read2_b32 v[72:73], v11 offset0:0 offset1:1
	ds_read2_b32 v[74:75], v11 offset0:2 offset1:3
	ds_read2_b32 v[76:77], v11 offset0:4 offset1:5
	ds_read2_b32 v[78:79], v11 offset0:6 offset1:7
	s_waitcnt lgkmcnt(4)
	v_cvt_pk_bf16_f32 v80, v64, v65
	v_cvt_pk_bf16_f32 v81, v66, v67
	v_cvt_pk_bf16_f32 v82, v68, v69
	v_cvt_pk_bf16_f32 v83, v70, v71
	global_store_dwordx4 v16, v[80:83], s[22:23]
	s_waitcnt lgkmcnt(0)
	v_cvt_pk_bf16_f32 v84, v72, v73
	v_cvt_pk_bf16_f32 v85, v74, v75
	v_cvt_pk_bf16_f32 v86, v76, v77
	v_cvt_pk_bf16_f32 v87, v78, v79
	global_store_dwordx4 v17, v[84:87], s[22:23]
.Lcl_done:
.LBB0_384:
	s_mov_b64 s[0:1], -1
